# MLA loop: 12 last-consumed exps of the even step deferred into the odd step's QK gaps (VALU/MFMA balance)
# speedup vs baseline: 1.0019x; 1.0019x over previous
; template <int DK, int PAR, bool HASNEXT, bool LDK, bool LDV, bool STK> ...
;     ...
;     __builtin_amdgcn_s_setprio(1);
;     if (LDK) { ldk0 = *(const u32x4*)(kg0 + (size_t)(t + 3) * kstep); if (has1) ldk1 = *(const u32x4*)(kg1 + (size_t)(t + 3) * kstep); }
;     if (LDV) ldv = *(const u32x4*)(vg + (size_t)(t + 2) * vstep);
;     bf16x8 kf[A::NDS][2];
;     if (HASNEXT) {
; #pragma unroll
;         for (int ds = 0; ds < A::NDS; ++ds) {
;             kf[ds][0] = *(const LAS bf16x8*)(Kb + aoffk + ds * 32);
;             kf[ds][1] = *(const LAS bf16x8*)(Kb + aoffk + 32 * A::KSTR + ds * 32);
;         }
;     }
;     s16x4 vlo[4][2], vhi[4][2];
; #pragma unroll
;     for (int j = 0; j < 2; ++j) {
;         vlo[j][0] = vtr(Vb + aoffv + j * 16 * A::VSTR); vhi[j][0] = vtr(Vb + aoffv + (j * 16 + 8) * A::VSTR);
;         vlo[j][1] = vtr(Vb + aoffv + j * 16 * A::VSTR + 64); vhi[j][1] = vtr(Vb + aoffv + (j * 16 + 8) * A::VSTR + 64);
;     }
;     if (HASNEXT) {
;         f32x16 z;
; #pragma unroll
;         for (int i = 0; i < 16; ++i) z[i] = 0.f;
; #pragma unroll
;         for (int ds = 0; ds < A::NDS; ++ds) {
;             N0 = __builtin_amdgcn_mfma_f32_32x32x16_bf16(kf[ds][0], qf[ds], ds == 0 ? z : N0, 0, 0, 0);
;             N1 = __builtin_amdgcn_mfma_f32_32x32x16_bf16(kf[ds][1], qf[ds], ds == 0 ? z : N1, 0, 0, 0);
;         }
;     }
; #pragma unroll
;     for (int i = 0; i < 16; ++i) { l += C0[i]; l += C1[i]; }
;     bf16x8 pb[4];
;     { u32x4 w;
;       w.x = pk2(C0[0], C0[1]); w.y = pk2(C0[2], C0[3]); w.z = pk2(C0[4], C0[5]); w.w = pk2(C0[6], C0[7]); pb[0] = __builtin_bit_cast(bf16x8, w);
;       w.x = pk2(C0[8], C0[9]); w.y = pk2(C0[10], C0[11]); w.z = pk2(C0[12], C0[13]); w.w = pk2(C0[14], C0[15]); pb[1] = __builtin_bit_cast(bf16x8, w);
;       w.x = pk2(C1[0], C1[1]); w.y = pk2(C1[2], C1[3]); w.z = pk2(C1[4], C1[5]); w.w = pk2(C1[6], C1[7]); pb[2] = __builtin_bit_cast(bf16x8, w);
;       w.x = pk2(C1[8], C1[9]); w.y = pk2(C1[10], C1[11]); w.z = pk2(C1[12], C1[13]); w.w = pk2(C1[14], C1[15]); pb[3] = __builtin_bit_cast(bf16x8, w); }
;     if (HASNEXT) {
;         constexpr int VPER = (DK == 64) ? 6 : 4;
; #pragma unroll
;         for (int g = 0; g < 2 * A::NDS; ++g) { __builtin_amdgcn_sched_group_barrier(0x008, 1, 0); __builtin_amdgcn_sched_group_barrier(0x002, VPER, 0); }
;     }
;     asm volatile("" : "+v"(l));
;     __builtin_amdgcn_sched_barrier(0);
.LBB0_765:
	s_or_b64 exec, exec, s[10:11]
	ds_read_b64_tr_b16 v[204:205], v172 offset:26624
	ds_read_b64_tr_b16 v[206:207], v172 offset:28160
	ds_read_b64_tr_b16 v[212:213], v172 offset:29696
	ds_read_b64_tr_b16 v[214:215], v172 offset:31232
	v_lshl_add_u64 v[80:81], s[50:51], 0, v[168:169]
	v_add_co_u32_e32 v94, vcc, 0x14f30000, v80
	v_add_f32_e32 v96, v185, v48
	s_nop 0
	v_addc_co_u32_e32 v95, vcc, 0, v81, vcc
	global_load_dwordx4 v[144:147], v[94:95], off offset:128
	v_mfma_f32_32x32x16_bf16 v[48:63], v[220:223], v[120:123], 0
	v_add_f32_e32 v96, v183, v96
	v_add_f32_e32 v96, v187, v96
	v_add_f32_e32 v96, v184, v96
	v_add_f32_e32 v96, v186, v96
	v_mfma_f32_32x32x16_bf16 v[32:47], v[224:227], v[116:119], v[32:47]
	v_add_f32_e32 v96, v82, v96
	v_add_f32_e32 v96, v189, v96
	v_add_f32_e32 v96, v83, v96
	v_add_f32_e32 v96, v188, v96
	v_mfma_f32_32x32x16_bf16 v[48:63], v[228:231], v[116:119], v[48:63]
	s_waitcnt vmcnt(3)
	ds_write_b128 v173, v[132:135] offset:13312
	s_and_saveexec_b64 s[10:11], s[6:7]
	ds_write_b128 v182, v[128:131] offset:13312
	s_or_b64 exec, exec, s[10:11]
	s_waitcnt vmcnt(2)
	ds_write_b128 v170, v[136:139] offset:38912
	v_add_f32_e32 v94, v84, v96
	v_add_f32_e32 v94, v190, v94
	v_add_f32_e32 v94, v85, v94
	v_add_f32_e32 v94, v192, v94
	v_mfma_f32_32x32x16_bf16 v[32:47], v[236:239], v[112:115], v[32:47]
	v_add_f32_e32 v94, v86, v94
	v_add_f32_e32 v94, v194, v94
	v_add_f32_e32 v94, v87, v94
	v_add_f32_e32 v94, v191, v94
	v_mfma_f32_32x32x16_bf16 v[48:63], v[240:243], v[112:115], v[48:63]
	v_add_f32_e32 v94, v72, v94
	v_add_f32_e32 v94, v193, v94
	v_add_f32_e32 v94, v73, v94
	v_add_f32_e32 v94, v88, v94
	v_mfma_f32_32x32x16_bf16 v[32:47], v[244:247], v[108:111], v[32:47]
	v_add_f32_e32 v94, v74, v94
	v_add_f32_e32 v94, v90, v94
	v_add_f32_e32 v94, v75, v94
	v_add_f32_e32 v94, v89, v94
	v_mfma_f32_32x32x16_bf16 v[48:63], v[248:251], v[108:111], v[48:63]
	v_add_f32_e32 v94, v76, v94
	v_add_f32_e32 v94, v91, v94
	v_add_f32_e32 v94, v77, v94
	v_add_f32_e32 v94, v92, v94
	v_mfma_f32_32x32x16_bf16 v[32:47], v[68:71], v[104:107], v[32:47]
	v_add_f32_e32 v94, v78, v94
	v_add_f32_e32 v94, v93, v94
	v_add_f32_e32 v94, v79, v94
	v_cvt_pk_bf16_f32 v216, v185, v187
	v_mfma_f32_32x32x16_bf16 v[48:63], v[196:199], v[104:107], v[48:63]
	v_cvt_pk_bf16_f32 v217, v186, v189
	v_cvt_pk_bf16_f32 v218, v188, v190
	v_cvt_pk_bf16_f32 v219, v192, v194
	v_cvt_pk_bf16_f32 v186, v191, v193
	ds_read_b64_tr_b16 v[196:197], v172 offset:26688
	ds_read_b64_tr_b16 v[198:199], v172 offset:28224
	ds_read_b64_tr_b16 v[190:191], v172 offset:29760
	v_mfma_f32_32x32x16_bf16 v[32:47], v[200:203], v[100:103], v[32:47]
	v_cvt_pk_bf16_f32 v187, v88, v90
	v_cvt_pk_bf16_f32 v188, v89, v91
	v_cvt_pk_bf16_f32 v189, v92, v93
	v_cvt_pk_bf16_f32 v88, v183, v184
	ds_read_b64_tr_b16 v[192:193], v172 offset:31296
	v_mfma_f32_32x32x16_bf16 v[48:63], v[208:211], v[100:103], v[48:63]
	v_cvt_pk_bf16_f32 v89, v82, v83
	v_cvt_pk_bf16_f32 v90, v84, v85
	v_cvt_pk_bf16_f32 v91, v86, v87
	v_cvt_pk_bf16_f32 v68, v72, v73
	v_cvt_pk_bf16_f32 v69, v74, v75
	v_cvt_pk_bf16_f32 v70, v76, v77
	v_cvt_pk_bf16_f32 v71, v78, v79
	s_waitcnt lgkmcnt(9)
	v_mfma_f32_32x32x16_bf16 v[16:31], v[204:207], v[216:219], v[16:31]
	ds_read_b64_tr_b16 v[72:73], v172 offset:32768
	ds_read_b64_tr_b16 v[74:75], v172 offset:34304
	ds_read_b64_tr_b16 v[76:77], v172 offset:32832
	ds_read_b64_tr_b16 v[78:79], v172 offset:34368
	v_exp_f32_e32 v96, v32
	v_exp_f32_e32 v99, v33
	v_exp_f32_e32 v150, v34
	s_waitcnt lgkmcnt(6)
	v_mfma_f32_32x32x16_bf16 v[0:15], v[196:199], v[216:219], v[0:15]
	v_exp_f32_e32 v152, v35
	v_exp_f32_e32 v154, v36
	v_exp_f32_e32 v184, v39
	v_mfma_f32_32x32x16_bf16 v[16:31], v[212:215], v[186:189], v[16:31]
	v_exp_f32_e32 v185, v40
	v_exp_f32_e32 v155, v52
	v_exp_f32_e32 v52, v37
	s_waitcnt lgkmcnt(4)
	v_mfma_f32_32x32x16_bf16 v[0:15], v[190:193], v[186:189], v[0:15]
	ds_read_b128 v[216:219], v181
	ds_read_b128 v[220:223], v181 offset:6656
	ds_read_b128 v[224:227], v181 offset:32
	v_exp_f32_e32 v180, v53
	v_exp_f32_e32 v53, v38
	v_exp_f32_e32 v98, v48
	s_waitcnt lgkmcnt(5)
	v_mfma_f32_32x32x16_bf16 v[16:31], v[72:75], v[88:91], v[16:31]
	ds_read_b64_tr_b16 v[72:73], v172 offset:35840
	ds_read_b64_tr_b16 v[74:75], v172 offset:37376
	ds_read_b128 v[228:231], v181 offset:6688
	ds_read_b128 v[236:239], v181 offset:64
	ds_read_b128 v[240:243], v181 offset:6720
	v_exp_f32_e32 v49, v49
	v_exp_f32_e32 v151, v50
	v_exp_f32_e32 v153, v51
	s_waitcnt lgkmcnt(8)
	v_mfma_f32_32x32x16_bf16 v[0:15], v[76:79], v[88:91], v[0:15]
	ds_read_b64_tr_b16 v[76:77], v172 offset:35904
	ds_read_b64_tr_b16 v[78:79], v172 offset:37440
	ds_read_b128 v[244:247], v181 offset:96
	ds_read_b128 v[248:251], v181 offset:6752
	ds_read_b128 v[32:35], v181 offset:128
	v_exp_f32_e32 v183, v54
	v_exp_f32_e32 v187, v55
	s_waitcnt lgkmcnt(8)
	v_mfma_f32_32x32x16_bf16 v[16:31], v[72:75], v[68:71], v[16:31]
	ds_read_b128 v[36:39], v181 offset:6784
	ds_read_b128 v[196:199], v181 offset:160
	ds_read_b128 v[200:203], v181 offset:6816
	v_exp_f32_e32 v188, v56
	v_exp_f32_e32 v56, v41
	s_waitcnt lgkmcnt(6)
	v_mfma_f32_32x32x16_bf16 v[0:15], v[76:79], v[68:71], v[0:15]
	v_exp_f32_e32 v189, v57
	s_setprio 0
	s_waitcnt lgkmcnt(0)
	s_barrier
	s_setprio 1
	v_add_co_u32_e32 v66, vcc, 0x2a5ba000, v66
	s_nop 1
	v_addc_co_u32_e32 v67, vcc, 0, v67, vcc
	global_load_dwordx4 v[132:135], v[66:67], off
	s_and_saveexec_b64 s[10:11], s[6:7]
	s_cbranch_execz .LBB0_769
	v_add_co_u32_e32 v64, vcc, 0x2a5ba000, v64
	s_nop 1
	v_addc_co_u32_e32 v65, vcc, 0, v65, vcc
	global_load_dwordx4 v[128:131], v[64:65], off
; template <int DK, int PAR, bool HASNEXT, bool LDK, bool LDV, bool STK> ...
;     ...
;     __builtin_amdgcn_s_setprio(1);
;     if (LDK) { ldk0 = *(const u32x4*)(kg0 + (size_t)(t + 3) * kstep); if (has1) ldk1 = *(const u32x4*)(kg1 + (size_t)(t + 3) * kstep); }
;     if (LDV) ldv = *(const u32x4*)(vg + (size_t)(t + 2) * vstep);
;     bf16x8 kf[A::NDS][2];
;     if (HASNEXT) {
; #pragma unroll
;         for (int ds = 0; ds < A::NDS; ++ds) {
;             kf[ds][0] = *(const LAS bf16x8*)(Kb + aoffk + ds * 32);
;             kf[ds][1] = *(const LAS bf16x8*)(Kb + aoffk + 32 * A::KSTR + ds * 32);
;         }
;     }
;     s16x4 vlo[4][2], vhi[4][2];
; #pragma unroll
;     for (int j = 0; j < 2; ++j) {
;         vlo[j][0] = vtr(Vb + aoffv + j * 16 * A::VSTR); vhi[j][0] = vtr(Vb + aoffv + (j * 16 + 8) * A::VSTR);
;         vlo[j][1] = vtr(Vb + aoffv + j * 16 * A::VSTR + 64); vhi[j][1] = vtr(Vb + aoffv + (j * 16 + 8) * A::VSTR + 64);
;     }
;     if (HASNEXT) {
;         f32x16 z;
; #pragma unroll
;         for (int i = 0; i < 16; ++i) z[i] = 0.f;
; #pragma unroll
;         for (int ds = 0; ds < A::NDS; ++ds) {
;             N0 = __builtin_amdgcn_mfma_f32_32x32x16_bf16(kf[ds][0], qf[ds], ds == 0 ? z : N0, 0, 0, 0);
;             N1 = __builtin_amdgcn_mfma_f32_32x32x16_bf16(kf[ds][1], qf[ds], ds == 0 ? z : N1, 0, 0, 0);
;         }
;     }
; #pragma unroll
;     for (int i = 0; i < 16; ++i) { l += C0[i]; l += C1[i]; }
;     bf16x8 pb[4];
;     { u32x4 w;
;       w.x = pk2(C0[0], C0[1]); w.y = pk2(C0[2], C0[3]); w.z = pk2(C0[4], C0[5]); w.w = pk2(C0[6], C0[7]); pb[0] = __builtin_bit_cast(bf16x8, w);
;       w.x = pk2(C0[8], C0[9]); w.y = pk2(C0[10], C0[11]); w.z = pk2(C0[12], C0[13]); w.w = pk2(C0[14], C0[15]); pb[1] = __builtin_bit_cast(bf16x8, w);
;       w.x = pk2(C1[0], C1[1]); w.y = pk2(C1[2], C1[3]); w.z = pk2(C1[4], C1[5]); w.w = pk2(C1[6], C1[7]); pb[2] = __builtin_bit_cast(bf16x8, w);
;       w.x = pk2(C1[8], C1[9]); w.y = pk2(C1[10], C1[11]); w.z = pk2(C1[12], C1[13]); w.w = pk2(C1[14], C1[15]); pb[3] = __builtin_bit_cast(bf16x8, w); }
;     if (HASNEXT) {
;         constexpr int VPER = (DK == 64) ? 6 : 4;
; #pragma unroll
;         for (int g = 0; g < 2 * A::NDS; ++g) { __builtin_amdgcn_sched_group_barrier(0x008, 1, 0); __builtin_amdgcn_sched_group_barrier(0x002, VPER, 0); }
;     }
;     asm volatile("" : "+v"(l));
;     __builtin_amdgcn_sched_barrier(0);
.LBB0_769:
	s_or_b64 exec, exec, s[10:11]
	s_mov_b32 s10, 0x14f48000
	v_mfma_f32_32x32x16_bf16 v[64:79], v[216:219], v[120:123], 0
	v_exp_f32_e32 v57, v42
	v_exp_f32_e32 v190, v58
	v_add_co_u32_e32 v40, vcc, s10, v80
	s_nop 0
	v_addc_co_u32_e32 v41, vcc, 0, v81, vcc
	global_load_dwordx4 v[136:139], v[40:41], off offset:128
	v_add_f32_e32 v48, v96, v94
	v_add_f32_e32 v48, v98, v48
	v_mfma_f32_32x32x16_bf16 v[80:95], v[220:223], v[120:123], 0
	v_exp_f32_e32 v186, v43
	v_exp_f32_e32 v191, v59
	v_add_f32_e32 v40, v99, v48
	v_add_f32_e32 v40, v49, v40
	v_add_f32_e32 v40, v150, v40
	v_add_f32_e32 v40, v151, v40
	v_mfma_f32_32x32x16_bf16 v[64:79], v[224:227], v[116:119], v[64:79]
	v_exp_f32_e32 v192, v44
	v_exp_f32_e32 v193, v60
	v_add_f32_e32 v40, v152, v40
	v_add_f32_e32 v40, v153, v40
	v_add_f32_e32 v40, v154, v40
	v_add_f32_e32 v40, v155, v40
	v_mfma_f32_32x32x16_bf16 v[80:95], v[228:231], v[116:119], v[80:95]
	v_exp_f32_e32 v60, v45
	v_exp_f32_e32 v194, v61
	s_waitcnt vmcnt(3)
	ds_write_b128 v173, v[140:143]
	s_and_saveexec_b64 s[10:11], s[6:7]
	ds_write_b128 v182, v[124:127]
	s_or_b64 exec, exec, s[10:11]
	s_waitcnt vmcnt(2)
	ds_write_b128 v170, v[144:147] offset:26624
	v_add_f32_e32 v40, v52, v40
	v_add_f32_e32 v40, v180, v40
	v_add_f32_e32 v40, v53, v40
	v_add_f32_e32 v40, v183, v40
	v_mfma_f32_32x32x16_bf16 v[64:79], v[236:239], v[112:115], v[64:79]
	v_exp_f32_e32 v61, v46
	v_exp_f32_e32 v62, v62
	v_add_f32_e32 v40, v184, v40
	v_add_f32_e32 v40, v187, v40
	v_add_f32_e32 v40, v185, v40
	v_add_f32_e32 v40, v188, v40
	v_mfma_f32_32x32x16_bf16 v[80:95], v[240:243], v[112:115], v[80:95]
	v_exp_f32_e32 v195, v47
	v_exp_f32_e32 v63, v63
	v_add_f32_e32 v40, v56, v40
	v_add_f32_e32 v40, v189, v40
	v_add_f32_e32 v40, v57, v40
	v_add_f32_e32 v40, v190, v40
	v_mfma_f32_32x32x16_bf16 v[64:79], v[244:247], v[108:111], v[64:79]
	v_add_f32_e32 v40, v186, v40
	v_add_f32_e32 v40, v191, v40
	v_add_f32_e32 v40, v192, v40
	v_add_f32_e32 v44, v193, v40
	v_mfma_f32_32x32x16_bf16 v[80:95], v[248:251], v[108:111], v[80:95]
	v_add_f32_e32 v44, v60, v44
	v_add_f32_e32 v44, v194, v44
	v_add_f32_e32 v44, v61, v44
	v_add_f32_e32 v48, v62, v44
	v_mfma_f32_32x32x16_bf16 v[64:79], v[32:35], v[104:107], v[64:79]
	v_add_f32_e32 v48, v195, v48
	v_add_f32_e32 v48, v63, v48
	v_cvt_pk_bf16_f32 v50, v96, v99
	v_cvt_pk_bf16_f32 v51, v150, v152
	ds_read_b64_tr_b16 v[44:45], v172 offset:38912
	ds_read_b64_tr_b16 v[46:47], v172 offset:40448
	v_mfma_f32_32x32x16_bf16 v[80:95], v[36:39], v[104:107], v[80:95]
	v_cvt_pk_bf16_f32 v52, v154, v52
	v_cvt_pk_bf16_f32 v53, v53, v184
	v_cvt_pk_bf16_f32 v58, v185, v56
	v_cvt_pk_bf16_f32 v59, v57, v186
	ds_read_b64_tr_b16 v[36:37], v172 offset:38976
	ds_read_b64_tr_b16 v[38:39], v172 offset:40512
	ds_read_b64_tr_b16 v[54:55], v172 offset:41984
	v_mfma_f32_32x32x16_bf16 v[64:79], v[196:199], v[100:103], v[64:79]
	v_cvt_pk_bf16_f32 v60, v192, v60
	v_cvt_pk_bf16_f32 v61, v61, v195
	v_cvt_pk_bf16_f32 v184, v98, v49
	v_cvt_pk_bf16_f32 v185, v151, v153
	ds_read_b64_tr_b16 v[56:57], v172 offset:43520
	ds_read_b64_tr_b16 v[40:41], v172 offset:42048
	ds_read_b64_tr_b16 v[42:43], v172 offset:43584
	v_mfma_f32_32x32x16_bf16 v[80:95], v[200:203], v[100:103], v[80:95]
	v_cvt_pk_bf16_f32 v186, v155, v180
	v_cvt_pk_bf16_f32 v187, v183, v187
	v_cvt_pk_bf16_f32 v32, v188, v189
	v_cvt_pk_bf16_f32 v33, v190, v191
	v_cvt_pk_bf16_f32 v34, v193, v194
	v_cvt_pk_bf16_f32 v35, v62, v63
	s_waitcnt lgkmcnt(6)
	v_mfma_f32_32x32x16_bf16 v[16:31], v[44:47], v[50:53], v[16:31]
	v_exp_f32_e32 v189, v67
	v_exp_f32_e32 v188, v68
	v_exp_f32_e32 v190, v69
	v_exp_f32_e32 v192, v70
	s_waitcnt lgkmcnt(4)
	v_mfma_f32_32x32x16_bf16 v[0:15], v[36:39], v[50:53], v[0:15]
	ds_read_b64_tr_b16 v[36:37], v172 offset:45056
	ds_read_b64_tr_b16 v[38:39], v172 offset:46592
	v_exp_f32_e32 v194, v71
	v_exp_f32_e32 v191, v72
	v_exp_f32_e32 v193, v73
	v_exp_f32_e32 v183, v80
	s_waitcnt lgkmcnt(4)
	v_mfma_f32_32x32x16_bf16 v[16:31], v[54:57], v[58:61], v[16:31]
	v_exp_f32_e32 v82, v82
	v_exp_f32_e32 v83, v83
	v_exp_f32_e32 v84, v84
	v_exp_f32_e32 v85, v85
	s_waitcnt lgkmcnt(2)
	v_mfma_f32_32x32x16_bf16 v[0:15], v[40:43], v[58:61], v[0:15]
	ds_read_b64_tr_b16 v[40:41], v172 offset:45120
	ds_read_b64_tr_b16 v[42:43], v172 offset:46656
	ds_read_b128 v[216:219], v181 offset:13312
	ds_read_b128 v[220:223], v181 offset:19968
	ds_read_b128 v[224:227], v181 offset:13344
	v_exp_f32_e32 v86, v86
	v_exp_f32_e32 v87, v87
	v_exp_f32_e32 v72, v88
	v_exp_f32_e32 v73, v89
	s_waitcnt lgkmcnt(5)
	v_mfma_f32_32x32x16_bf16 v[16:31], v[36:39], v[184:187], v[16:31]
	ds_read_b64_tr_b16 v[36:37], v172 offset:48128
	ds_read_b64_tr_b16 v[38:39], v172 offset:49664
	ds_read_b128 v[228:231], v181 offset:20000
	ds_read_b128 v[236:239], v181 offset:13376
	ds_read_b128 v[240:243], v181 offset:20032
	v_exp_f32_e32 v88, v74
	v_exp_f32_e32 v74, v90
	v_exp_f32_e32 v90, v75
	v_exp_f32_e32 v75, v91
	s_waitcnt lgkmcnt(8)
	v_mfma_f32_32x32x16_bf16 v[0:15], v[40:43], v[184:187], v[0:15]
	ds_read_b64_tr_b16 v[40:41], v172 offset:48192
	ds_read_b64_tr_b16 v[42:43], v172 offset:49728
	ds_read_b128 v[244:247], v181 offset:13408
	ds_read_b128 v[248:251], v181 offset:20064
	ds_read_b128 v[68:71], v181 offset:13440
	v_exp_f32_e32 v89, v76
	v_exp_f32_e32 v76, v92
	v_exp_f32_e32 v91, v77
	v_exp_f32_e32 v77, v93
	s_waitcnt lgkmcnt(8)
	v_mfma_f32_32x32x16_bf16 v[16:31], v[36:39], v[32:35], v[16:31]
	ds_read_b128 v[196:199], v181 offset:20096
	ds_read_b128 v[200:203], v181 offset:13472
	ds_read_b128 v[208:211], v181 offset:20128
	v_exp_f32_e32 v92, v78
	v_exp_f32_e32 v78, v94
	v_exp_f32_e32 v93, v79
	v_exp_f32_e32 v79, v95
	s_waitcnt lgkmcnt(6)
	v_mfma_f32_32x32x16_bf16 v[0:15], v[40:43], v[32:35], v[0:15]
	v_exp_f32_e32 v185, v64
	v_exp_f32_e32 v187, v65
	v_exp_f32_e32 v184, v81
	v_exp_f32_e32 v186, v66
	s_setprio 0
	s_waitcnt lgkmcnt(0)
	s_barrier
	s_add_i32 s12, s12, 2
	s_mov_b64 s[10:11], 0x30000
	v_lshl_add_u64 v[164:165], v[164:165], 0, s[72:73]
	v_lshl_add_u64 v[166:167], v[166:167], 0, s[72:73]
	s_cmpk_lt_u32 s12, 0x7e
	v_lshl_add_u64 v[168:169], v[168:169], 0, s[10:11]
	s_cbranch_scc1 .LBB0_763
	s_branch .LBB0_781
